# best + P1 gate epilogue: second bias pair loaded together with the first
# speedup vs baseline: 1.0046x; 1.0046x over previous
.LBB0_135:
	s_add_i32 s6, s90, -10
	v_lshl_or_b32 v138, s6, 8, v181
	v_lshl_add_u64 v[176:177], v[138:139], 2, s[48:49]
	global_load_dwordx4 v[156:159], v[176:177], off offset:16
	global_load_dwordx4 v[160:163], v[176:177], off
	global_load_dwordx4 v[226:229], v[176:177], off offset:528
	global_load_dwordx4 v[230:233], v[176:177], off offset:512
	s_lshl_b32 s7, s6, 4
	s_and_b32 s7, s7, 0x3fffffc0
	s_add_i32 s7, s7, s38
	s_lshl_b32 s7, s7, 2
	s_and_b32 s6, s6, 3
	s_or_b32 s6, s7, s6
	s_ashr_i32 s7, s6, 31
	s_lshl_b64 s[6:7], s[6:7], 16
	s_waitcnt vmcnt(2)
	v_pk_mul_f32 v[164:165], v[158:159], s[96:97] op_sel_hi:[1,0]
	v_pk_mul_f32 v[168:169], v[156:157], s[96:97] op_sel_hi:[1,0]
	s_nop 0
	s_nop 0
	v_pk_mul_f32 v[170:171], v[160:161], s[96:97] op_sel_hi:[1,0]
	v_fmamk_f32 v56, v56, 0xbfb8aa3b, v168
	v_fmamk_f32 v120, v120, 0xbfb8aa3b, v168
	v_fmamk_f32 v104, v104, 0xbfb8aa3b, v168
	v_fmamk_f32 v88, v88, 0xbfb8aa3b, v168
	v_fmamk_f32 v72, v72, 0xbfb8aa3b, v168
	v_exp_f32_e32 v56, v56
	v_fmamk_f32 v57, v57, 0xbfb8aa3b, v169
	v_fmamk_f32 v40, v40, 0xbfb8aa3b, v168
	v_fmamk_f32 v24, v24, 0xbfb8aa3b, v168
	v_fmamk_f32 v8, v8, 0xbfb8aa3b, v168
	v_pk_mul_f32 v[166:167], v[162:163], s[96:97] op_sel_hi:[1,0]
	v_exp_f32_e32 v120, v120
	v_fmamk_f32 v121, v121, 0xbfb8aa3b, v169
	v_exp_f32_e32 v104, v104
	v_fmamk_f32 v105, v105, 0xbfb8aa3b, v169
	v_exp_f32_e32 v88, v88
	v_fmamk_f32 v89, v89, 0xbfb8aa3b, v169
	v_exp_f32_e32 v72, v72
	v_fmamk_f32 v73, v73, 0xbfb8aa3b, v169
	v_exp_f32_e32 v57, v57
	v_fmamk_f32 v58, v58, 0xbfb8aa3b, v164
	v_exp_f32_e32 v40, v40
	v_fmamk_f32 v41, v41, 0xbfb8aa3b, v169
	v_exp_f32_e32 v24, v24
	v_fmamk_f32 v25, v25, 0xbfb8aa3b, v169
	v_exp_f32_e32 v8, v8
	v_fmac_f32_e32 v169, 0xbfb8aa3b, v9
	v_exp_f32_e32 v121, v121
	v_fmamk_f32 v122, v122, 0xbfb8aa3b, v164
	v_exp_f32_e32 v105, v105
	v_fmamk_f32 v106, v106, 0xbfb8aa3b, v164
	v_exp_f32_e32 v89, v89
	v_fmamk_f32 v90, v90, 0xbfb8aa3b, v164
	v_exp_f32_e32 v73, v73
	v_fmamk_f32 v74, v74, 0xbfb8aa3b, v164
	v_exp_f32_e32 v58, v58
	v_exp_f32_e32 v41, v41
	v_fmamk_f32 v42, v42, 0xbfb8aa3b, v164
	v_exp_f32_e32 v25, v25
	v_fmamk_f32 v26, v26, 0xbfb8aa3b, v164
	v_exp_f32_e32 v9, v169
	v_exp_f32_e32 v122, v122
	v_exp_f32_e32 v106, v106
	v_exp_f32_e32 v90, v90
	v_exp_f32_e32 v74, v74
	v_exp_f32_e32 v42, v42
	v_exp_f32_e32 v26, v26
	v_fmamk_f32 v10, v10, 0xbfb8aa3b, v164
	v_fmamk_f32 v56, v56, 0x3b808081, v205
	v_exp_f32_e32 v10, v10
	v_fmamk_f32 v120, v120, 0x3b808081, v205
	v_fmamk_f32 v104, v104, 0x3b808081, v205
	v_fmamk_f32 v88, v88, 0x3b808081, v205
	v_fmamk_f32 v72, v72, 0x3b808081, v205
	v_rcp_f32_e32 v56, v56
	v_fmamk_f32 v57, v57, 0x3b808081, v205
	v_fmamk_f32 v40, v40, 0x3b808081, v205
	v_fmamk_f32 v24, v24, 0x3b808081, v205
	v_fmamk_f32 v8, v8, 0x3b808081, v205
	v_rcp_f32_e32 v120, v120
	v_fmamk_f32 v121, v121, 0x3b808081, v205
	v_rcp_f32_e32 v104, v104
	v_fmamk_f32 v105, v105, 0x3b808081, v205
	v_rcp_f32_e32 v88, v88
	v_fmamk_f32 v89, v89, 0x3b808081, v205
	v_rcp_f32_e32 v72, v72
	v_fmamk_f32 v73, v73, 0x3b808081, v205
	v_rcp_f32_e32 v57, v57
	v_fmamk_f32 v58, v58, 0x3b808081, v205
	v_rcp_f32_e32 v40, v40
	v_fmamk_f32 v41, v41, 0x3b808081, v205
	v_rcp_f32_e32 v24, v24
	v_fmamk_f32 v25, v25, 0x3b808081, v205
	v_rcp_f32_e32 v8, v8
	v_fmamk_f32 v9, v9, 0x3b808081, v205
	v_rcp_f32_e32 v121, v121
	v_fmamk_f32 v122, v122, 0x3b808081, v205
	s_waitcnt vmcnt(1)
	v_pk_mul_f32 v[160:161], v[226:227], s[96:97] op_sel_hi:[1,0]
	s_waitcnt vmcnt(0)
	v_pk_mul_f32 v[162:163], v[230:231], s[96:97] op_sel_hi:[1,0]
	v_fmamk_f32 v112, v112, 0xbfb8aa3b, v160
	v_fmamk_f32 v96, v96, 0xbfb8aa3b, v160
	v_fmamk_f32 v80, v80, 0xbfb8aa3b, v160
	v_fmamk_f32 v64, v64, 0xbfb8aa3b, v160
	v_fmamk_f32 v48, v48, 0xbfb8aa3b, v160
	v_fmamk_f32 v32, v32, 0xbfb8aa3b, v160
	v_fmamk_f32 v16, v16, 0xbfb8aa3b, v160
	v_fmamk_f32 v0, v0, 0xbfb8aa3b, v160
	v_pk_mul_f32 v[156:157], v[228:229], s[96:97] op_sel_hi:[1,0]
	v_exp_f32_e32 v112, v112
	v_fmamk_f32 v113, v113, 0xbfb8aa3b, v161
	v_exp_f32_e32 v96, v96
	v_fmamk_f32 v97, v97, 0xbfb8aa3b, v161
	v_exp_f32_e32 v80, v80
	v_fmamk_f32 v81, v81, 0xbfb8aa3b, v161
	v_exp_f32_e32 v64, v64
	v_fmamk_f32 v65, v65, 0xbfb8aa3b, v161
	v_exp_f32_e32 v48, v48
	v_fmamk_f32 v49, v49, 0xbfb8aa3b, v161
	v_exp_f32_e32 v32, v32
	v_fmamk_f32 v33, v33, 0xbfb8aa3b, v161
	v_exp_f32_e32 v16, v16
	v_fmamk_f32 v17, v17, 0xbfb8aa3b, v161
	v_exp_f32_e32 v0, v0
	v_fmac_f32_e32 v161, 0xbfb8aa3b, v1
	v_exp_f32_e32 v113, v113
	v_fmamk_f32 v114, v114, 0xbfb8aa3b, v156
	v_exp_f32_e32 v97, v97
	v_fmamk_f32 v98, v98, 0xbfb8aa3b, v156
	v_exp_f32_e32 v81, v81
	v_fmamk_f32 v82, v82, 0xbfb8aa3b, v156
	v_exp_f32_e32 v65, v65
	v_fmamk_f32 v66, v66, 0xbfb8aa3b, v156
	v_exp_f32_e32 v49, v49
	v_fmamk_f32 v50, v50, 0xbfb8aa3b, v156
	v_exp_f32_e32 v33, v33
	v_fmamk_f32 v34, v34, 0xbfb8aa3b, v156
	v_exp_f32_e32 v17, v17
	v_fmamk_f32 v18, v18, 0xbfb8aa3b, v156
	v_exp_f32_e32 v1, v161
	v_exp_f32_e32 v114, v114
	v_exp_f32_e32 v98, v98
	v_exp_f32_e32 v82, v82
	v_exp_f32_e32 v66, v66
	v_exp_f32_e32 v50, v50
	v_exp_f32_e32 v34, v34
	v_exp_f32_e32 v18, v18
	v_fmamk_f32 v2, v2, 0xbfb8aa3b, v156
	v_exp_f32_e32 v2, v2
	v_fmamk_f32 v112, v112, 0x3b808081, v205
	v_fmamk_f32 v96, v96, 0x3b808081, v205
	v_fmamk_f32 v80, v80, 0x3b808081, v205
	v_fmamk_f32 v64, v64, 0x3b808081, v205
	v_fmamk_f32 v48, v48, 0x3b808081, v205
	v_fmamk_f32 v32, v32, 0x3b808081, v205
	v_fmamk_f32 v16, v16, 0x3b808081, v205
	v_fmamk_f32 v0, v0, 0x3b808081, v205
	v_rcp_f32_e32 v112, v112
	v_fmamk_f32 v113, v113, 0x3b808081, v205
	v_rcp_f32_e32 v96, v96
	v_fmamk_f32 v97, v97, 0x3b808081, v205
	v_rcp_f32_e32 v80, v80
	v_fmamk_f32 v81, v81, 0x3b808081, v205
	v_rcp_f32_e32 v64, v64
	v_fmamk_f32 v65, v65, 0x3b808081, v205
	v_rcp_f32_e32 v48, v48
	v_fmamk_f32 v49, v49, 0x3b808081, v205
	v_rcp_f32_e32 v32, v32
	v_fmamk_f32 v33, v33, 0x3b808081, v205
	v_rcp_f32_e32 v16, v16
	v_fmamk_f32 v17, v17, 0x3b808081, v205
	v_rcp_f32_e32 v0, v0
	v_fmamk_f32 v1, v1, 0x3b808081, v205
	v_rcp_f32_e32 v113, v113
	v_fmamk_f32 v114, v114, 0x3b808081, v205
	v_rcp_f32_e32 v105, v105
	v_fmamk_f32 v106, v106, 0x3b808081, v205
	v_rcp_f32_e32 v97, v97
	v_fmamk_f32 v98, v98, 0x3b808081, v205
	v_rcp_f32_e32 v89, v89
	v_fmamk_f32 v90, v90, 0x3b808081, v205
	v_rcp_f32_e32 v81, v81
	v_fmamk_f32 v82, v82, 0x3b808081, v205
	v_rcp_f32_e32 v73, v73
	v_fmamk_f32 v74, v74, 0x3b808081, v205
	v_rcp_f32_e32 v65, v65
	v_fmamk_f32 v66, v66, 0x3b808081, v205
	v_rcp_f32_e32 v58, v58
	v_rcp_f32_e32 v49, v49
	v_fmamk_f32 v50, v50, 0x3b808081, v205
	v_rcp_f32_e32 v41, v41
	v_fmamk_f32 v42, v42, 0x3b808081, v205
	v_rcp_f32_e32 v33, v33
	v_fmamk_f32 v34, v34, 0x3b808081, v205
	v_rcp_f32_e32 v25, v25
	v_fmamk_f32 v26, v26, 0x3b808081, v205
	v_rcp_f32_e32 v17, v17
	v_fmamk_f32 v18, v18, 0x3b808081, v205
	v_rcp_f32_e32 v9, v9
	v_rcp_f32_e32 v1, v1
	v_rcp_f32_e32 v122, v122
	v_rcp_f32_e32 v114, v114
	v_rcp_f32_e32 v106, v106
	v_rcp_f32_e32 v98, v98
	v_rcp_f32_e32 v90, v90
	v_rcp_f32_e32 v82, v82
	v_rcp_f32_e32 v74, v74
	v_rcp_f32_e32 v66, v66
	v_rcp_f32_e32 v50, v50
	v_rcp_f32_e32 v42, v42
	v_rcp_f32_e32 v34, v34
	v_rcp_f32_e32 v26, v26
	v_rcp_f32_e32 v18, v18
	v_fmamk_f32 v10, v10, 0x3b808081, v205
	v_fmamk_f32 v2, v2, 0x3b808081, v205
	v_max_f32_e32 v56, 1.0, v56
	v_rcp_f32_e32 v10, v10
	v_rcp_f32_e32 v2, v2
	v_max_f32_e32 v120, 1.0, v120
	v_max_f32_e32 v112, 1.0, v112
	v_max_f32_e32 v104, 1.0, v104
	v_max_f32_e32 v96, 1.0, v96
	v_max_f32_e32 v88, 1.0, v88
	v_max_f32_e32 v80, 1.0, v80
	v_max_f32_e32 v72, 1.0, v72
	v_max_f32_e32 v64, 1.0, v64
	v_fmamk_f32 v60, v60, 0xbfb8aa3b, v170
	v_rndne_f32_e32 v56, v56
	v_max_f32_e32 v57, 1.0, v57
	v_max_f32_e32 v48, 1.0, v48
	v_max_f32_e32 v40, 1.0, v40
	v_max_f32_e32 v32, 1.0, v32
	v_max_f32_e32 v24, 1.0, v24
	v_max_f32_e32 v16, 1.0, v16
	v_max_f32_e32 v8, 1.0, v8
	v_max_f32_e32 v0, 1.0, v0
	v_fmamk_f32 v124, v124, 0xbfb8aa3b, v170
	v_rndne_f32_e32 v120, v120
	v_max_f32_e32 v121, 1.0, v121
	v_fmamk_f32 v116, v116, 0xbfb8aa3b, v162
	v_rndne_f32_e32 v112, v112
	v_max_f32_e32 v113, 1.0, v113
	v_fmamk_f32 v108, v108, 0xbfb8aa3b, v170
	v_rndne_f32_e32 v104, v104
	v_max_f32_e32 v105, 1.0, v105
	v_fmamk_f32 v100, v100, 0xbfb8aa3b, v162
	v_rndne_f32_e32 v96, v96
	v_max_f32_e32 v97, 1.0, v97
	v_fmamk_f32 v92, v92, 0xbfb8aa3b, v170
	v_rndne_f32_e32 v88, v88
	v_max_f32_e32 v89, 1.0, v89
	v_fmamk_f32 v84, v84, 0xbfb8aa3b, v162
	v_rndne_f32_e32 v80, v80
	v_max_f32_e32 v81, 1.0, v81
	v_fmamk_f32 v76, v76, 0xbfb8aa3b, v170
	v_rndne_f32_e32 v72, v72
	v_max_f32_e32 v73, 1.0, v73
	v_fmamk_f32 v68, v68, 0xbfb8aa3b, v162
	v_rndne_f32_e32 v64, v64
	v_max_f32_e32 v65, 1.0, v65
	v_exp_f32_e32 v60, v60
	v_cvt_pk_u8_f32 v56, v56, 0, 0
	v_fmamk_f32 v61, v61, 0xbfb8aa3b, v171
	v_rndne_f32_e32 v57, v57
	v_max_f32_e32 v58, 1.0, v58
	v_fmamk_f32 v52, v52, 0xbfb8aa3b, v162
	v_rndne_f32_e32 v48, v48
	v_max_f32_e32 v49, 1.0, v49
	v_fmamk_f32 v44, v44, 0xbfb8aa3b, v170
	v_rndne_f32_e32 v40, v40
	v_max_f32_e32 v41, 1.0, v41
	v_fmamk_f32 v36, v36, 0xbfb8aa3b, v162
	v_rndne_f32_e32 v32, v32
	v_max_f32_e32 v33, 1.0, v33
	v_fmamk_f32 v28, v28, 0xbfb8aa3b, v170
	v_rndne_f32_e32 v24, v24
	v_max_f32_e32 v25, 1.0, v25
	v_fmamk_f32 v20, v20, 0xbfb8aa3b, v162
	v_rndne_f32_e32 v16, v16
	v_max_f32_e32 v17, 1.0, v17
	v_fmamk_f32 v12, v12, 0xbfb8aa3b, v170
	v_rndne_f32_e32 v8, v8
	v_max_f32_e32 v9, 1.0, v9
	v_fmamk_f32 v4, v4, 0xbfb8aa3b, v162
	v_rndne_f32_e32 v0, v0
	v_max_f32_e32 v1, 1.0, v1
	v_pk_mul_f32 v[158:159], v[232:233], s[96:97] op_sel_hi:[1,0]
	v_exp_f32_e32 v124, v124
	v_cvt_pk_u8_f32 v120, v120, 0, 0
	v_fmamk_f32 v125, v125, 0xbfb8aa3b, v171
	v_rndne_f32_e32 v121, v121
	v_max_f32_e32 v122, 1.0, v122
	v_exp_f32_e32 v116, v116
	v_cvt_pk_u8_f32 v112, v112, 0, 0
	v_fmamk_f32 v117, v117, 0xbfb8aa3b, v163
	v_rndne_f32_e32 v113, v113
	v_max_f32_e32 v114, 1.0, v114
	v_exp_f32_e32 v108, v108
	v_cvt_pk_u8_f32 v104, v104, 0, 0
	v_fmamk_f32 v109, v109, 0xbfb8aa3b, v171
	v_rndne_f32_e32 v105, v105
	v_max_f32_e32 v106, 1.0, v106
	v_exp_f32_e32 v100, v100
	v_cvt_pk_u8_f32 v96, v96, 0, 0
	v_fmamk_f32 v101, v101, 0xbfb8aa3b, v163
	v_rndne_f32_e32 v97, v97
	v_max_f32_e32 v98, 1.0, v98
	v_exp_f32_e32 v92, v92
	v_cvt_pk_u8_f32 v88, v88, 0, 0
	v_fmamk_f32 v93, v93, 0xbfb8aa3b, v171
	v_rndne_f32_e32 v89, v89
	v_max_f32_e32 v90, 1.0, v90
	v_exp_f32_e32 v84, v84
	v_cvt_pk_u8_f32 v80, v80, 0, 0
	v_fmamk_f32 v85, v85, 0xbfb8aa3b, v163
	v_rndne_f32_e32 v81, v81
	v_max_f32_e32 v82, 1.0, v82
	v_exp_f32_e32 v76, v76
	v_cvt_pk_u8_f32 v72, v72, 0, 0
	v_fmamk_f32 v77, v77, 0xbfb8aa3b, v171
	v_rndne_f32_e32 v73, v73
	v_max_f32_e32 v74, 1.0, v74
	v_exp_f32_e32 v68, v68
	v_cvt_pk_u8_f32 v64, v64, 0, 0
	v_fmamk_f32 v69, v69, 0xbfb8aa3b, v163
	v_rndne_f32_e32 v65, v65
	v_max_f32_e32 v66, 1.0, v66
	v_exp_f32_e32 v61, v61
	v_cvt_pk_u8_f32 v56, v57, 1, v56
	v_fmamk_f32 v57, v62, 0xbfb8aa3b, v166
	v_rndne_f32_e32 v58, v58
	v_exp_f32_e32 v52, v52
	v_cvt_pk_u8_f32 v48, v48, 0, 0
	v_fmamk_f32 v53, v53, 0xbfb8aa3b, v163
	v_rndne_f32_e32 v49, v49
	v_max_f32_e32 v50, 1.0, v50
	v_exp_f32_e32 v44, v44
	v_cvt_pk_u8_f32 v40, v40, 0, 0
	v_fmamk_f32 v45, v45, 0xbfb8aa3b, v171
	v_rndne_f32_e32 v41, v41
	v_max_f32_e32 v42, 1.0, v42
	v_exp_f32_e32 v36, v36
	v_cvt_pk_u8_f32 v32, v32, 0, 0
	v_fmamk_f32 v37, v37, 0xbfb8aa3b, v163
	v_rndne_f32_e32 v33, v33
	v_max_f32_e32 v34, 1.0, v34
	v_exp_f32_e32 v28, v28
	v_cvt_pk_u8_f32 v24, v24, 0, 0
	v_fmamk_f32 v29, v29, 0xbfb8aa3b, v171
	v_rndne_f32_e32 v25, v25
	v_max_f32_e32 v26, 1.0, v26
	v_exp_f32_e32 v20, v20
	v_cvt_pk_u8_f32 v16, v16, 0, 0
	v_fmamk_f32 v21, v21, 0xbfb8aa3b, v163
	v_rndne_f32_e32 v17, v17
	v_max_f32_e32 v18, 1.0, v18
	v_exp_f32_e32 v12, v12
	v_cvt_pk_u8_f32 v8, v8, 0, 0
	v_fmac_f32_e32 v171, 0xbfb8aa3b, v13
	v_rndne_f32_e32 v9, v9
	v_exp_f32_e32 v4, v4
	v_cvt_pk_u8_f32 v0, v0, 0, 0
	v_fmac_f32_e32 v163, 0xbfb8aa3b, v5
	v_rndne_f32_e32 v1, v1
	v_exp_f32_e32 v125, v125
	v_cvt_pk_u8_f32 v120, v121, 1, v120
	v_fmamk_f32 v121, v126, 0xbfb8aa3b, v166
	v_rndne_f32_e32 v122, v122
	v_exp_f32_e32 v117, v117
	v_cvt_pk_u8_f32 v112, v113, 1, v112
	v_fmamk_f32 v113, v118, 0xbfb8aa3b, v158
	v_rndne_f32_e32 v114, v114
	v_exp_f32_e32 v109, v109
	v_cvt_pk_u8_f32 v104, v105, 1, v104
	v_fmamk_f32 v105, v110, 0xbfb8aa3b, v166
	v_rndne_f32_e32 v106, v106
	v_exp_f32_e32 v101, v101
	v_cvt_pk_u8_f32 v96, v97, 1, v96
	v_fmamk_f32 v97, v102, 0xbfb8aa3b, v158
	v_rndne_f32_e32 v98, v98
	v_exp_f32_e32 v93, v93
	v_cvt_pk_u8_f32 v88, v89, 1, v88
	v_fmamk_f32 v89, v94, 0xbfb8aa3b, v166
	v_rndne_f32_e32 v90, v90
	v_exp_f32_e32 v85, v85
	v_cvt_pk_u8_f32 v80, v81, 1, v80
	v_fmamk_f32 v81, v86, 0xbfb8aa3b, v158
	v_rndne_f32_e32 v82, v82
	v_exp_f32_e32 v77, v77
	v_cvt_pk_u8_f32 v72, v73, 1, v72
	v_fmamk_f32 v73, v78, 0xbfb8aa3b, v166
	v_rndne_f32_e32 v74, v74
	v_exp_f32_e32 v69, v69
	v_cvt_pk_u8_f32 v64, v65, 1, v64
	v_fmamk_f32 v65, v70, 0xbfb8aa3b, v158
	v_rndne_f32_e32 v66, v66
	v_exp_f32_e32 v57, v57
	v_cvt_pk_u8_f32 v58, v58, 2, v56
	v_fmamk_f32 v56, v63, 0xbfb8aa3b, v167
	v_fmamk_f32 v59, v59, 0xbfb8aa3b, v165
	v_exp_f32_e32 v53, v53
	v_cvt_pk_u8_f32 v48, v49, 1, v48
	v_fmamk_f32 v49, v54, 0xbfb8aa3b, v158
	v_rndne_f32_e32 v50, v50
	v_fmamk_f32 v51, v51, 0xbfb8aa3b, v157
	v_exp_f32_e32 v45, v45
	v_cvt_pk_u8_f32 v40, v41, 1, v40
	v_fmamk_f32 v41, v46, 0xbfb8aa3b, v166
	v_rndne_f32_e32 v42, v42
	v_exp_f32_e32 v37, v37
	v_cvt_pk_u8_f32 v32, v33, 1, v32
	v_fmamk_f32 v33, v38, 0xbfb8aa3b, v158
	v_rndne_f32_e32 v34, v34
	v_exp_f32_e32 v29, v29
	v_cvt_pk_u8_f32 v24, v25, 1, v24
	v_fmamk_f32 v25, v30, 0xbfb8aa3b, v166
	v_rndne_f32_e32 v26, v26
	v_exp_f32_e32 v21, v21
	v_cvt_pk_u8_f32 v16, v17, 1, v16
	v_fmamk_f32 v17, v22, 0xbfb8aa3b, v158
	v_rndne_f32_e32 v18, v18
	v_exp_f32_e32 v13, v171
	v_cvt_pk_u8_f32 v8, v9, 1, v8
	v_fmamk_f32 v9, v14, 0xbfb8aa3b, v166
	v_max_f32_e32 v10, 1.0, v10
	v_exp_f32_e32 v5, v163
	v_cvt_pk_u8_f32 v0, v1, 1, v0
	v_fmamk_f32 v1, v6, 0xbfb8aa3b, v158
	v_max_f32_e32 v2, 1.0, v2
	v_exp_f32_e32 v121, v121
	v_cvt_pk_u8_f32 v122, v122, 2, v120
	v_fmamk_f32 v120, v127, 0xbfb8aa3b, v167
	v_fmamk_f32 v123, v123, 0xbfb8aa3b, v165
	v_exp_f32_e32 v113, v113
	v_cvt_pk_u8_f32 v112, v114, 2, v112
	v_fmamk_f32 v114, v119, 0xbfb8aa3b, v159
	v_fmamk_f32 v115, v115, 0xbfb8aa3b, v157
	v_exp_f32_e32 v105, v105
	v_cvt_pk_u8_f32 v106, v106, 2, v104
	v_fmamk_f32 v104, v111, 0xbfb8aa3b, v167
	v_fmamk_f32 v107, v107, 0xbfb8aa3b, v165
	v_exp_f32_e32 v97, v97
	v_cvt_pk_u8_f32 v96, v98, 2, v96
	v_fmamk_f32 v98, v103, 0xbfb8aa3b, v159
	v_fmamk_f32 v99, v99, 0xbfb8aa3b, v157
	v_exp_f32_e32 v89, v89
	v_cvt_pk_u8_f32 v90, v90, 2, v88
	v_fmamk_f32 v88, v95, 0xbfb8aa3b, v167
	v_fmamk_f32 v91, v91, 0xbfb8aa3b, v165
	v_exp_f32_e32 v81, v81
	v_cvt_pk_u8_f32 v80, v82, 2, v80
	v_fmamk_f32 v82, v87, 0xbfb8aa3b, v159
	v_fmamk_f32 v83, v83, 0xbfb8aa3b, v157
	v_exp_f32_e32 v73, v73
	v_cvt_pk_u8_f32 v74, v74, 2, v72
	v_fmamk_f32 v72, v79, 0xbfb8aa3b, v167
	v_fmamk_f32 v75, v75, 0xbfb8aa3b, v165
	v_exp_f32_e32 v65, v65
	v_cvt_pk_u8_f32 v64, v66, 2, v64
	v_fmamk_f32 v66, v71, 0xbfb8aa3b, v159
	v_fmamk_f32 v67, v67, 0xbfb8aa3b, v157
	v_exp_f32_e32 v56, v56
	v_exp_f32_e32 v59, v59
	v_exp_f32_e32 v49, v49
	v_cvt_pk_u8_f32 v48, v50, 2, v48
	v_fmamk_f32 v50, v55, 0xbfb8aa3b, v159
	v_exp_f32_e32 v51, v51
	v_exp_f32_e32 v41, v41
	v_cvt_pk_u8_f32 v42, v42, 2, v40
	v_fmamk_f32 v40, v47, 0xbfb8aa3b, v167
	v_fmamk_f32 v43, v43, 0xbfb8aa3b, v165
	v_exp_f32_e32 v33, v33
	v_cvt_pk_u8_f32 v32, v34, 2, v32
	v_fmamk_f32 v34, v39, 0xbfb8aa3b, v159
	v_fmamk_f32 v35, v35, 0xbfb8aa3b, v157
	v_exp_f32_e32 v25, v25
	v_cvt_pk_u8_f32 v26, v26, 2, v24
	v_fmamk_f32 v24, v31, 0xbfb8aa3b, v167
	v_fmamk_f32 v27, v27, 0xbfb8aa3b, v165
	v_exp_f32_e32 v17, v17
	v_cvt_pk_u8_f32 v16, v18, 2, v16
	v_fmamk_f32 v18, v23, 0xbfb8aa3b, v159
	v_fmamk_f32 v19, v19, 0xbfb8aa3b, v157
	v_exp_f32_e32 v9, v9
	v_rndne_f32_e32 v10, v10
	v_fmac_f32_e32 v167, 0xbfb8aa3b, v15
	v_fmac_f32_e32 v165, 0xbfb8aa3b, v11
	v_exp_f32_e32 v1, v1
	v_rndne_f32_e32 v2, v2
	v_fmac_f32_e32 v159, 0xbfb8aa3b, v7
	v_fmac_f32_e32 v157, 0xbfb8aa3b, v3
	v_exp_f32_e32 v120, v120
	v_exp_f32_e32 v123, v123
	v_exp_f32_e32 v114, v114
	v_exp_f32_e32 v115, v115
	v_exp_f32_e32 v104, v104
	v_exp_f32_e32 v107, v107
	v_exp_f32_e32 v98, v98
	v_exp_f32_e32 v99, v99
	v_exp_f32_e32 v88, v88
	v_exp_f32_e32 v91, v91
	v_exp_f32_e32 v82, v82
	v_exp_f32_e32 v83, v83
	v_exp_f32_e32 v72, v72
	v_exp_f32_e32 v75, v75
	v_exp_f32_e32 v66, v66
	v_exp_f32_e32 v67, v67
	v_fmamk_f32 v60, v60, 0x3b808081, v205
	v_exp_f32_e32 v50, v50
	v_exp_f32_e32 v40, v40
	v_exp_f32_e32 v43, v43
	v_exp_f32_e32 v34, v34
	v_exp_f32_e32 v35, v35
	v_exp_f32_e32 v24, v24
	v_exp_f32_e32 v27, v27
	v_exp_f32_e32 v18, v18
	v_exp_f32_e32 v19, v19
	v_cvt_pk_u8_f32 v10, v10, 2, v8
	v_exp_f32_e32 v8, v167
	v_exp_f32_e32 v11, v165
	v_cvt_pk_u8_f32 v0, v2, 2, v0
	v_exp_f32_e32 v2, v159
	v_exp_f32_e32 v3, v157
	v_fmamk_f32 v124, v124, 0x3b808081, v205
	v_fmamk_f32 v116, v116, 0x3b808081, v205
	v_fmamk_f32 v108, v108, 0x3b808081, v205
	v_fmamk_f32 v100, v100, 0x3b808081, v205
	v_fmamk_f32 v92, v92, 0x3b808081, v205
	v_fmamk_f32 v84, v84, 0x3b808081, v205
	v_fmamk_f32 v76, v76, 0x3b808081, v205
	v_fmamk_f32 v68, v68, 0x3b808081, v205
	v_rcp_f32_e32 v60, v60
	v_fmamk_f32 v61, v61, 0x3b808081, v205
	v_fmamk_f32 v52, v52, 0x3b808081, v205
	v_fmamk_f32 v44, v44, 0x3b808081, v205
	v_fmamk_f32 v36, v36, 0x3b808081, v205
	v_fmamk_f32 v28, v28, 0x3b808081, v205
	v_fmamk_f32 v20, v20, 0x3b808081, v205
	v_fmamk_f32 v12, v12, 0x3b808081, v205
	v_fmamk_f32 v4, v4, 0x3b808081, v205
	v_rcp_f32_e32 v124, v124
	v_fmamk_f32 v125, v125, 0x3b808081, v205
	v_rcp_f32_e32 v116, v116
	v_fmamk_f32 v117, v117, 0x3b808081, v205
	v_rcp_f32_e32 v108, v108
	v_fmamk_f32 v109, v109, 0x3b808081, v205
	v_rcp_f32_e32 v100, v100
	v_fmamk_f32 v101, v101, 0x3b808081, v205
	v_rcp_f32_e32 v92, v92
	v_fmamk_f32 v93, v93, 0x3b808081, v205
	v_rcp_f32_e32 v84, v84
	v_fmamk_f32 v85, v85, 0x3b808081, v205
	v_rcp_f32_e32 v76, v76
	v_fmamk_f32 v77, v77, 0x3b808081, v205
	v_rcp_f32_e32 v68, v68
	v_fmamk_f32 v69, v69, 0x3b808081, v205
	v_rcp_f32_e32 v61, v61
	v_fmamk_f32 v57, v57, 0x3b808081, v205
	v_rcp_f32_e32 v52, v52
	v_fmamk_f32 v53, v53, 0x3b808081, v205
	v_rcp_f32_e32 v44, v44
	v_fmamk_f32 v45, v45, 0x3b808081, v205
	v_rcp_f32_e32 v36, v36
	v_fmamk_f32 v37, v37, 0x3b808081, v205
	v_rcp_f32_e32 v28, v28
	v_fmamk_f32 v29, v29, 0x3b808081, v205
	v_rcp_f32_e32 v20, v20
	v_fmamk_f32 v21, v21, 0x3b808081, v205
	v_rcp_f32_e32 v12, v12
	v_fmamk_f32 v13, v13, 0x3b808081, v205
	v_rcp_f32_e32 v4, v4
	v_fmamk_f32 v5, v5, 0x3b808081, v205
	v_rcp_f32_e32 v125, v125
	v_fmamk_f32 v121, v121, 0x3b808081, v205
	v_rcp_f32_e32 v117, v117
	v_fmamk_f32 v113, v113, 0x3b808081, v205
	v_rcp_f32_e32 v109, v109
	v_fmamk_f32 v105, v105, 0x3b808081, v205
	v_rcp_f32_e32 v101, v101
	v_fmamk_f32 v97, v97, 0x3b808081, v205
	v_rcp_f32_e32 v93, v93
	v_fmamk_f32 v89, v89, 0x3b808081, v205
	v_rcp_f32_e32 v85, v85
	v_fmamk_f32 v81, v81, 0x3b808081, v205
	v_rcp_f32_e32 v77, v77
	v_fmamk_f32 v73, v73, 0x3b808081, v205
	v_rcp_f32_e32 v69, v69
	v_fmamk_f32 v65, v65, 0x3b808081, v205
	v_rcp_f32_e32 v57, v57
	v_fmamk_f32 v56, v56, 0x3b808081, v205
	v_fmamk_f32 v59, v59, 0x3b808081, v205
	v_rcp_f32_e32 v53, v53
	v_fmamk_f32 v49, v49, 0x3b808081, v205
	v_fmamk_f32 v51, v51, 0x3b808081, v205
	v_rcp_f32_e32 v45, v45
	v_fmamk_f32 v41, v41, 0x3b808081, v205
	v_rcp_f32_e32 v37, v37
	v_fmamk_f32 v33, v33, 0x3b808081, v205
	v_rcp_f32_e32 v29, v29
	v_fmamk_f32 v25, v25, 0x3b808081, v205
	v_rcp_f32_e32 v21, v21
	v_fmamk_f32 v17, v17, 0x3b808081, v205
	v_rcp_f32_e32 v13, v13
	v_fmamk_f32 v9, v9, 0x3b808081, v205
	v_rcp_f32_e32 v5, v5
	v_fmamk_f32 v1, v1, 0x3b808081, v205
	v_rcp_f32_e32 v121, v121
	v_fmamk_f32 v120, v120, 0x3b808081, v205
	v_fmamk_f32 v123, v123, 0x3b808081, v205
	v_rcp_f32_e32 v113, v113
	v_fmamk_f32 v114, v114, 0x3b808081, v205
	v_fmamk_f32 v115, v115, 0x3b808081, v205
	v_rcp_f32_e32 v105, v105
	v_fmamk_f32 v104, v104, 0x3b808081, v205
	v_fmamk_f32 v107, v107, 0x3b808081, v205
	v_rcp_f32_e32 v97, v97
	v_fmamk_f32 v98, v98, 0x3b808081, v205
	v_fmamk_f32 v99, v99, 0x3b808081, v205
	v_rcp_f32_e32 v89, v89
	v_fmamk_f32 v88, v88, 0x3b808081, v205
	v_fmamk_f32 v91, v91, 0x3b808081, v205
	v_rcp_f32_e32 v81, v81
	v_fmamk_f32 v82, v82, 0x3b808081, v205
	v_fmamk_f32 v83, v83, 0x3b808081, v205
	v_rcp_f32_e32 v73, v73
	v_fmamk_f32 v72, v72, 0x3b808081, v205
	v_fmamk_f32 v75, v75, 0x3b808081, v205
	v_rcp_f32_e32 v65, v65
	v_fmamk_f32 v66, v66, 0x3b808081, v205
	v_fmamk_f32 v67, v67, 0x3b808081, v205
	v_rcp_f32_e32 v56, v56
	v_rcp_f32_e32 v59, v59
	v_rcp_f32_e32 v49, v49
	v_fmamk_f32 v50, v50, 0x3b808081, v205
	v_rcp_f32_e32 v51, v51
	v_rcp_f32_e32 v41, v41
	v_fmamk_f32 v40, v40, 0x3b808081, v205
	v_fmamk_f32 v43, v43, 0x3b808081, v205
	v_rcp_f32_e32 v33, v33
	v_fmamk_f32 v34, v34, 0x3b808081, v205
	v_fmamk_f32 v35, v35, 0x3b808081, v205
	v_rcp_f32_e32 v25, v25
	v_fmamk_f32 v24, v24, 0x3b808081, v205
	v_fmamk_f32 v27, v27, 0x3b808081, v205
	v_rcp_f32_e32 v17, v17
	v_fmamk_f32 v18, v18, 0x3b808081, v205
	v_fmamk_f32 v19, v19, 0x3b808081, v205
	v_rcp_f32_e32 v9, v9
	v_fmamk_f32 v8, v8, 0x3b808081, v205
	v_fmamk_f32 v11, v11, 0x3b808081, v205
	v_rcp_f32_e32 v1, v1
	v_fmamk_f32 v2, v2, 0x3b808081, v205
	v_fmamk_f32 v3, v3, 0x3b808081, v205
	v_rcp_f32_e32 v120, v120
	v_rcp_f32_e32 v123, v123
	v_rcp_f32_e32 v114, v114
	v_rcp_f32_e32 v115, v115
	v_rcp_f32_e32 v104, v104
	v_rcp_f32_e32 v107, v107
	v_rcp_f32_e32 v98, v98
	v_rcp_f32_e32 v99, v99
	v_rcp_f32_e32 v88, v88
	v_rcp_f32_e32 v91, v91
	v_rcp_f32_e32 v82, v82
	v_rcp_f32_e32 v83, v83
	v_rcp_f32_e32 v72, v72
	v_rcp_f32_e32 v75, v75
	v_rcp_f32_e32 v66, v66
	v_rcp_f32_e32 v67, v67
	v_max_f32_e32 v60, 1.0, v60
	v_rcp_f32_e32 v50, v50
	v_rcp_f32_e32 v40, v40
	v_rcp_f32_e32 v43, v43
	v_rcp_f32_e32 v34, v34
	v_rcp_f32_e32 v35, v35
	v_rcp_f32_e32 v24, v24
	v_rcp_f32_e32 v27, v27
	v_rcp_f32_e32 v18, v18
	v_rcp_f32_e32 v19, v19
	v_rcp_f32_e32 v8, v8
	v_rcp_f32_e32 v11, v11
	v_rcp_f32_e32 v2, v2
	v_rcp_f32_e32 v3, v3
	v_max_f32_e32 v124, 1.0, v124
	v_max_f32_e32 v116, 1.0, v116
	v_max_f32_e32 v108, 1.0, v108
	v_max_f32_e32 v100, 1.0, v100
	v_max_f32_e32 v92, 1.0, v92
	v_max_f32_e32 v84, 1.0, v84
	v_max_f32_e32 v76, 1.0, v76
	v_max_f32_e32 v68, 1.0, v68
	v_rndne_f32_e32 v60, v60
	v_max_f32_e32 v61, 1.0, v61
	v_max_f32_e32 v52, 1.0, v52
	v_max_f32_e32 v44, 1.0, v44
	v_max_f32_e32 v36, 1.0, v36
	v_max_f32_e32 v28, 1.0, v28
	v_max_f32_e32 v20, 1.0, v20
	v_max_f32_e32 v12, 1.0, v12
	v_max_f32_e32 v4, 1.0, v4
	v_rndne_f32_e32 v124, v124
	v_max_f32_e32 v125, 1.0, v125
	v_rndne_f32_e32 v116, v116
	v_max_f32_e32 v117, 1.0, v117
	v_rndne_f32_e32 v108, v108
	v_max_f32_e32 v109, 1.0, v109
	v_rndne_f32_e32 v100, v100
	v_max_f32_e32 v101, 1.0, v101
	v_rndne_f32_e32 v92, v92
	v_max_f32_e32 v93, 1.0, v93
	v_rndne_f32_e32 v84, v84
	v_max_f32_e32 v85, 1.0, v85
	v_rndne_f32_e32 v76, v76
	v_max_f32_e32 v77, 1.0, v77
	v_rndne_f32_e32 v68, v68
	v_max_f32_e32 v69, 1.0, v69
	v_cvt_pk_u8_f32 v60, v60, 0, 0
	v_rndne_f32_e32 v61, v61
	v_max_f32_e32 v57, 1.0, v57
	v_rndne_f32_e32 v52, v52
	v_max_f32_e32 v53, 1.0, v53
	v_rndne_f32_e32 v44, v44
	v_max_f32_e32 v45, 1.0, v45
	v_rndne_f32_e32 v36, v36
	v_max_f32_e32 v37, 1.0, v37
	v_rndne_f32_e32 v28, v28
	v_max_f32_e32 v29, 1.0, v29
	v_rndne_f32_e32 v20, v20
	v_max_f32_e32 v21, 1.0, v21
	v_rndne_f32_e32 v12, v12
	v_max_f32_e32 v13, 1.0, v13
	v_rndne_f32_e32 v4, v4
	v_max_f32_e32 v5, 1.0, v5
	v_cvt_pk_u8_f32 v124, v124, 0, 0
	v_rndne_f32_e32 v125, v125
	v_max_f32_e32 v121, 1.0, v121
	v_cvt_pk_u8_f32 v116, v116, 0, 0
	v_rndne_f32_e32 v117, v117
	v_max_f32_e32 v113, 1.0, v113
	v_cvt_pk_u8_f32 v108, v108, 0, 0
	v_rndne_f32_e32 v109, v109
	v_max_f32_e32 v105, 1.0, v105
	v_cvt_pk_u8_f32 v100, v100, 0, 0
	v_rndne_f32_e32 v101, v101
	v_max_f32_e32 v97, 1.0, v97
	v_cvt_pk_u8_f32 v92, v92, 0, 0
	v_rndne_f32_e32 v93, v93
	v_max_f32_e32 v89, 1.0, v89
	v_cvt_pk_u8_f32 v84, v84, 0, 0
	v_rndne_f32_e32 v85, v85
	v_max_f32_e32 v81, 1.0, v81
	v_cvt_pk_u8_f32 v76, v76, 0, 0
	v_rndne_f32_e32 v77, v77
	v_max_f32_e32 v73, 1.0, v73
	v_cvt_pk_u8_f32 v68, v68, 0, 0
	v_rndne_f32_e32 v69, v69
	v_max_f32_e32 v65, 1.0, v65
	v_cvt_pk_u8_f32 v60, v61, 1, v60
	v_rndne_f32_e32 v57, v57
	v_max_f32_e32 v56, 1.0, v56
	v_max_f32_e32 v59, 1.0, v59
	v_cvt_pk_u8_f32 v52, v52, 0, 0
	v_rndne_f32_e32 v53, v53
	v_max_f32_e32 v49, 1.0, v49
	v_max_f32_e32 v51, 1.0, v51
	v_cvt_pk_u8_f32 v44, v44, 0, 0
	v_rndne_f32_e32 v45, v45
	v_max_f32_e32 v41, 1.0, v41
	v_cvt_pk_u8_f32 v36, v36, 0, 0
	v_rndne_f32_e32 v37, v37
	v_max_f32_e32 v33, 1.0, v33
	v_cvt_pk_u8_f32 v28, v28, 0, 0
	v_rndne_f32_e32 v29, v29
	v_max_f32_e32 v25, 1.0, v25
	v_cvt_pk_u8_f32 v20, v20, 0, 0
	v_rndne_f32_e32 v21, v21
	v_max_f32_e32 v17, 1.0, v17
	v_cvt_pk_u8_f32 v12, v12, 0, 0
	v_rndne_f32_e32 v13, v13
	v_max_f32_e32 v9, 1.0, v9
	v_cvt_pk_u8_f32 v4, v4, 0, 0
	v_rndne_f32_e32 v5, v5
	v_max_f32_e32 v1, 1.0, v1
	v_lshl_add_u64 v[172:173], v[140:141], 0, s[6:7]
	v_cvt_pk_u8_f32 v124, v125, 1, v124
	v_rndne_f32_e32 v121, v121
	v_max_f32_e32 v120, 1.0, v120
	v_max_f32_e32 v123, 1.0, v123
	v_cvt_pk_u8_f32 v116, v117, 1, v116
	v_rndne_f32_e32 v113, v113
	v_max_f32_e32 v114, 1.0, v114
	v_max_f32_e32 v115, 1.0, v115
	v_cvt_pk_u8_f32 v108, v109, 1, v108
	v_rndne_f32_e32 v105, v105
	v_max_f32_e32 v104, 1.0, v104
	v_max_f32_e32 v107, 1.0, v107
	v_cvt_pk_u8_f32 v100, v101, 1, v100
	v_rndne_f32_e32 v97, v97
	v_max_f32_e32 v98, 1.0, v98
	v_max_f32_e32 v99, 1.0, v99
	v_cvt_pk_u8_f32 v92, v93, 1, v92
	v_rndne_f32_e32 v89, v89
	v_max_f32_e32 v88, 1.0, v88
	v_max_f32_e32 v91, 1.0, v91
	v_cvt_pk_u8_f32 v84, v85, 1, v84
	v_rndne_f32_e32 v81, v81
	v_max_f32_e32 v82, 1.0, v82
	v_max_f32_e32 v83, 1.0, v83
	v_cvt_pk_u8_f32 v76, v77, 1, v76
	v_rndne_f32_e32 v73, v73
	v_max_f32_e32 v72, 1.0, v72
	v_max_f32_e32 v75, 1.0, v75
	v_cvt_pk_u8_f32 v68, v69, 1, v68
	v_rndne_f32_e32 v65, v65
	v_max_f32_e32 v66, 1.0, v66
	v_max_f32_e32 v67, 1.0, v67
	v_cvt_pk_u8_f32 v57, v57, 2, v60
	v_rndne_f32_e32 v56, v56
	v_rndne_f32_e32 v59, v59
	v_cvt_pk_u8_f32 v52, v53, 1, v52
	v_rndne_f32_e32 v49, v49
	v_max_f32_e32 v50, 1.0, v50
	v_rndne_f32_e32 v51, v51
	s_movk_i32 s6, 0x1000
	v_cvt_pk_u8_f32 v44, v45, 1, v44
	v_rndne_f32_e32 v41, v41
	v_max_f32_e32 v40, 1.0, v40
	v_max_f32_e32 v43, 1.0, v43
	v_cvt_pk_u8_f32 v36, v37, 1, v36
	v_rndne_f32_e32 v33, v33
	v_max_f32_e32 v34, 1.0, v34
	v_max_f32_e32 v35, 1.0, v35
	v_cvt_pk_u8_f32 v28, v29, 1, v28
	v_rndne_f32_e32 v25, v25
	v_max_f32_e32 v24, 1.0, v24
	v_max_f32_e32 v27, 1.0, v27
	v_cvt_pk_u8_f32 v20, v21, 1, v20
	v_rndne_f32_e32 v17, v17
	v_max_f32_e32 v18, 1.0, v18
	v_max_f32_e32 v19, 1.0, v19
	v_cvt_pk_u8_f32 v12, v13, 1, v12
	v_rndne_f32_e32 v9, v9
	v_max_f32_e32 v8, 1.0, v8
	v_max_f32_e32 v11, 1.0, v11
	v_cvt_pk_u8_f32 v4, v5, 1, v4
	v_rndne_f32_e32 v1, v1
	v_max_f32_e32 v2, 1.0, v2
	v_max_f32_e32 v3, 1.0, v3
	v_cvt_pk_u8_f32 v121, v121, 2, v124
	v_rndne_f32_e32 v120, v120
	v_rndne_f32_e32 v123, v123
	v_cvt_pk_u8_f32 v113, v113, 2, v116
	v_rndne_f32_e32 v114, v114
	v_rndne_f32_e32 v115, v115
	v_cvt_pk_u8_f32 v105, v105, 2, v108
	v_rndne_f32_e32 v104, v104
	v_rndne_f32_e32 v107, v107
	v_cvt_pk_u8_f32 v97, v97, 2, v100
	v_rndne_f32_e32 v98, v98
	v_rndne_f32_e32 v99, v99
	v_cvt_pk_u8_f32 v89, v89, 2, v92
	v_rndne_f32_e32 v88, v88
	v_rndne_f32_e32 v91, v91
	v_cvt_pk_u8_f32 v81, v81, 2, v84
	v_rndne_f32_e32 v82, v82
	v_rndne_f32_e32 v83, v83
	v_cvt_pk_u8_f32 v73, v73, 2, v76
	v_rndne_f32_e32 v72, v72
	v_rndne_f32_e32 v75, v75
	v_cvt_pk_u8_f32 v65, v65, 2, v68
	v_rndne_f32_e32 v66, v66
	v_rndne_f32_e32 v67, v67
	v_cvt_pk_u8_f32 v56, v56, 3, v57
	v_cvt_pk_u8_f32 v57, v59, 3, v58
	v_cvt_pk_u8_f32 v49, v49, 2, v52
	v_rndne_f32_e32 v50, v50
	v_cvt_pk_u8_f32 v59, v51, 3, v48
	v_add_co_u32_e32 v48, vcc, s6, v172
	v_cvt_pk_u8_f32 v41, v41, 2, v44
	v_rndne_f32_e32 v40, v40
	v_rndne_f32_e32 v43, v43
	v_cvt_pk_u8_f32 v33, v33, 2, v36
	v_rndne_f32_e32 v34, v34
	v_rndne_f32_e32 v35, v35
	v_cvt_pk_u8_f32 v25, v25, 2, v28
	v_rndne_f32_e32 v24, v24
	v_rndne_f32_e32 v27, v27
	v_cvt_pk_u8_f32 v17, v17, 2, v20
	v_rndne_f32_e32 v18, v18
	v_rndne_f32_e32 v19, v19
	v_cvt_pk_u8_f32 v9, v9, 2, v12
	v_rndne_f32_e32 v8, v8
	v_rndne_f32_e32 v11, v11
	v_cvt_pk_u8_f32 v1, v1, 2, v4
	v_rndne_f32_e32 v2, v2
	v_rndne_f32_e32 v3, v3
	v_cvt_pk_u8_f32 v120, v120, 3, v121
	v_cvt_pk_u8_f32 v121, v123, 3, v122
	v_cvt_pk_u8_f32 v122, v114, 3, v113
	v_cvt_pk_u8_f32 v123, v115, 3, v112
	v_cvt_pk_u8_f32 v104, v104, 3, v105
	v_cvt_pk_u8_f32 v105, v107, 3, v106
	v_cvt_pk_u8_f32 v106, v98, 3, v97
	v_cvt_pk_u8_f32 v107, v99, 3, v96
	v_cvt_pk_u8_f32 v88, v88, 3, v89
	v_cvt_pk_u8_f32 v89, v91, 3, v90
	v_cvt_pk_u8_f32 v90, v82, 3, v81
	v_cvt_pk_u8_f32 v91, v83, 3, v80
	v_cvt_pk_u8_f32 v72, v72, 3, v73
	v_cvt_pk_u8_f32 v73, v75, 3, v74
	v_cvt_pk_u8_f32 v74, v66, 3, v65
	v_cvt_pk_u8_f32 v75, v67, 3, v64
	v_cvt_pk_u8_f32 v58, v50, 3, v49
	v_addc_co_u32_e32 v49, vcc, 0, v173, vcc
	v_cvt_pk_u8_f32 v40, v40, 3, v41
	v_cvt_pk_u8_f32 v41, v43, 3, v42
	v_cvt_pk_u8_f32 v42, v34, 3, v33
	v_cvt_pk_u8_f32 v43, v35, 3, v32
	v_cvt_pk_u8_f32 v24, v24, 3, v25
	v_cvt_pk_u8_f32 v25, v27, 3, v26
	v_cvt_pk_u8_f32 v26, v18, 3, v17
	v_cvt_pk_u8_f32 v27, v19, 3, v16
	v_cvt_pk_u8_f32 v8, v8, 3, v9
	v_cvt_pk_u8_f32 v9, v11, 3, v10
	v_cvt_pk_u8_f32 v10, v2, 3, v1
	v_cvt_pk_u8_f32 v11, v3, 3, v0
	global_store_dwordx4 v[172:173], v[120:123], off
	global_store_dwordx4 v[172:173], v[104:107], off offset:1024
	global_store_dwordx4 v[172:173], v[88:91], off offset:2048
	global_store_dwordx4 v[172:173], v[72:75], off offset:3072
	global_store_dwordx4 v[48:49], v[56:59], off
	global_store_dwordx4 v[48:49], v[40:43], off offset:1024
	global_store_dwordx4 v[48:49], v[24:27], off offset:2048
	global_store_dwordx4 v[48:49], v[8:11], off offset:3072
